# grid barrier: the last XCD leader adds every XCD's generation word itself (non-leader workgroups released one hand-off hop earlier); not on barrier 7
# speedup vs baseline: 1.0171x; 1.0103x over previous
; __device__ __forceinline__ unsigned xb_ld(unsigned* p)              { return __hip_atomic_load(p, __ATOMIC_RELAXED, __HIP_MEMORY_SCOPE_AGENT); }
; __device__ __forceinline__ unsigned xb_add(unsigned* p, unsigned v) { return __hip_atomic_fetch_add(p, v, __ATOMIC_RELAXED, __HIP_MEMORY_SCOPE_AGENT); }
; #define XB_SPIN(cond, bar) do { unsigned _sp = 0; while (cond) { __builtin_amdgcn_s_sleep(1); \
;     if ((++_sp & 255u) == 0u) { if (xb_ld(&(bar)[XB_TMO])) break; if (_sp > XB_SPIN_CAP) { atomicAdd(&(bar)[XB_TMO], 1u); break; } } } } while (0)
; __device__ __forceinline__ void xcd_barrier(const XcdBarrier& b) {
;     ...
;         const unsigned old = xb_add(&bar[XB_XSUB(b.x)], 1u);
;         const unsigned gen = old / nloc;
;         if (old + 1u == (gen + 1u) * nloc) {
;             __builtin_amdgcn_fence(__ATOMIC_RELEASE, "agent");
;             asm volatile("s_waitcnt vmcnt(0)" ::: "memory");
;             const unsigned og = xb_add(&bar[XB_TOP], 1u);
;             const unsigned tg = og / nx;
;             if (og + 1u == (tg + 1u) * nx) xb_add(&bar[XB_TOPGEN], 1u);
;             else XB_SPIN(xb_ld(&bar[XB_TOPGEN]) == tg, bar);
;             __builtin_amdgcn_fence(__ATOMIC_ACQUIRE, "agent");
;             xb_add(&bar[XB_XGEN(b.x)], 1u);
;             asm volatile("s_waitcnt vmcnt(0)" ::: "memory");
.LBB0_83:
	s_or_b64 exec, exec, s[8:9]
	v_cvt_f32_u32_e32 v3, v0
	s_waitcnt vmcnt(0)
	v_readfirstlane_b32 s3, v2
	s_add_u32 s8, s68, 0x83500
	s_addc_u32 s9, s69, 0
	v_rcp_iflag_f32_e32 v3, v3
	v_add_u32_e32 v1, s3, v1
	v_add_u32_e32 v4, 1, v1
	s_mov_b64 s[12:13], -1
	v_mul_f32_e32 v2, 0x4f7ffffe, v3
	v_cvt_u32_f32_e32 v2, v2
	v_sub_u32_e32 v3, 0, v0
	v_mul_lo_u32 v3, v3, v2
	v_mul_hi_u32 v3, v2, v3
	v_add_u32_e32 v2, v2, v3
	v_mul_hi_u32 v2, v1, v2
	v_mul_lo_u32 v3, v2, v0
	v_sub_u32_e32 v1, v1, v3
	v_add_u32_e32 v5, 1, v2
	v_cmp_ge_u32_e32 vcc, v1, v0
	v_sub_u32_e32 v3, v1, v0
	s_nop 0
	v_cndmask_b32_e32 v2, v2, v5, vcc
	v_cndmask_b32_e32 v1, v1, v3, vcc
	v_add_u32_e32 v3, 1, v2
	v_cmp_ge_u32_e32 vcc, v1, v0
	s_nop 1
	v_cndmask_b32_e32 v2, v2, v3, vcc
	v_mul_lo_u32 v1, v0, v2
	v_add_u32_e32 v0, v1, v0
	v_cmp_ne_u32_e32 vcc, v4, v0
	v_mov_b64_e32 v[0:1], s[8:9]
	s_cbranch_vccnz .Lxg_1
	v_mov_b32_e32 v5, 1
	v_mov_b32_e32 v3, 0x82400
	global_atomic_add v3, v5, s[68:69]
	v_add_u32_e32 v3, 0x100, v3
	global_atomic_add v3, v5, s[68:69]
	v_add_u32_e32 v3, 0x100, v3
	global_atomic_add v3, v5, s[68:69]
	v_add_u32_e32 v3, 0x100, v3
	global_atomic_add v3, v5, s[68:69]
	v_add_u32_e32 v3, 0x100, v3
	global_atomic_add v3, v5, s[68:69]
	v_add_u32_e32 v3, 0x100, v3
	global_atomic_add v3, v5, s[68:69]
	v_add_u32_e32 v3, 0x100, v3
	global_atomic_add v3, v5, s[68:69]
	v_add_u32_e32 v3, 0x100, v3
	global_atomic_add v3, v5, s[68:69]
	v_add_u32_e32 v3, 0x100, v3
	global_atomic_add v3, v5, s[68:69]
	v_add_u32_e32 v3, 0x100, v3
	global_atomic_add v3, v5, s[68:69]
	v_add_u32_e32 v3, 0x100, v3
	global_atomic_add v3, v5, s[68:69]
	v_add_u32_e32 v3, 0x100, v3
	global_atomic_add v3, v5, s[68:69]
	v_add_u32_e32 v3, 0x100, v3
	global_atomic_add v3, v5, s[68:69]
	v_add_u32_e32 v3, 0x100, v3
	global_atomic_add v3, v5, s[68:69]
	v_add_u32_e32 v3, 0x100, v3
	global_atomic_add v3, v5, s[68:69]
	v_add_u32_e32 v3, 0x100, v3
	global_atomic_add v3, v5, s[68:69]
.Lxg_1:
	s_and_saveexec_b64 s[6:7], vcc
	s_cbranch_execz .LBB0_95
	v_mov_b32_e32 v0, 0
	global_load_dword v1, v0, s[8:9] sc1
	s_mov_b64 s[16:17], 0
	s_waitcnt vmcnt(0)
	v_cmp_eq_u32_e32 vcc, v1, v2
	s_and_saveexec_b64 s[14:15], vcc
	s_cbranch_execz .LBB0_94
	s_add_u32 s12, s68, 0x80200
	s_addc_u32 s13, s69, 0
	s_mov_b32 s3, 1
	s_branch .LBB0_87

; __device__ __forceinline__ unsigned xb_add(unsigned* p, unsigned v) { return __hip_atomic_fetch_add(p, v, __ATOMIC_RELAXED, __HIP_MEMORY_SCOPE_AGENT); }
; __device__ __forceinline__ void xcd_barrier(const XcdBarrier& b) {
;     ...
;             xb_add(&bar[XB_XGEN(b.x)], 1u);
;             asm volatile("s_waitcnt vmcnt(0)" ::: "memory");
.LBB0_97:
	s_or_b64 exec, exec, s[6:7]
	s_mov_b64 s[6:7], exec
	v_mbcnt_lo_u32_b32 v0, s6, 0
	v_mbcnt_hi_u32_b32 v0, s7, v0
	v_cmp_eq_u32_e32 vcc, 0, v0
	s_waitcnt vmcnt(0)
	s_and_saveexec_b64 s[8:9], vcc
	s_cbranch_execz .LBB0_99
	s_bcnt1_i32_b64 s3, s[6:7]
	v_mov_b32_e32 v0, 0x2000
	v_mov_b32_e32 v1, s3
	s_nop 0

; __device__ __forceinline__ unsigned xb_ld(unsigned* p)              { return __hip_atomic_load(p, __ATOMIC_RELAXED, __HIP_MEMORY_SCOPE_AGENT); }
; __device__ __forceinline__ unsigned xb_add(unsigned* p, unsigned v) { return __hip_atomic_fetch_add(p, v, __ATOMIC_RELAXED, __HIP_MEMORY_SCOPE_AGENT); }
; #define XB_SPIN(cond, bar) do { unsigned _sp = 0; while (cond) { __builtin_amdgcn_s_sleep(1); \
;     if ((++_sp & 255u) == 0u) { if (xb_ld(&(bar)[XB_TMO])) break; if (_sp > XB_SPIN_CAP) { atomicAdd(&(bar)[XB_TMO], 1u); break; } } } } while (0)
; __device__ __forceinline__ void xcd_barrier(const XcdBarrier& b) {
;     ...
;         const unsigned old = xb_add(&bar[XB_XSUB(b.x)], 1u);
;         const unsigned gen = old / nloc;
;         if (old + 1u == (gen + 1u) * nloc) {
;             __builtin_amdgcn_fence(__ATOMIC_RELEASE, "agent");
;             asm volatile("s_waitcnt vmcnt(0)" ::: "memory");
;             const unsigned og = xb_add(&bar[XB_TOP], 1u);
;             const unsigned tg = og / nx;
;             if (og + 1u == (tg + 1u) * nx) xb_add(&bar[XB_TOPGEN], 1u);
;             else XB_SPIN(xb_ld(&bar[XB_TOPGEN]) == tg, bar);
;             __builtin_amdgcn_fence(__ATOMIC_ACQUIRE, "agent");
;             xb_add(&bar[XB_XGEN(b.x)], 1u);
;             asm volatile("s_waitcnt vmcnt(0)" ::: "memory");
.LBB0_653:
	s_or_b64 exec, exec, s[8:9]
	v_cvt_f32_u32_e32 v3, v0
	s_waitcnt vmcnt(0)
	v_readfirstlane_b32 s3, v2
	s_add_u32 s8, s68, 0x83500
	s_addc_u32 s9, s69, 0
	v_rcp_iflag_f32_e32 v3, v3
	v_add_u32_e32 v1, s3, v1
	v_add_u32_e32 v4, 1, v1
	s_mov_b64 s[10:11], -1
	v_mul_f32_e32 v2, 0x4f7ffffe, v3
	v_cvt_u32_f32_e32 v2, v2
	v_sub_u32_e32 v3, 0, v0
	v_mul_lo_u32 v3, v3, v2
	v_mul_hi_u32 v3, v2, v3
	v_add_u32_e32 v2, v2, v3
	v_mul_hi_u32 v2, v1, v2
	v_mul_lo_u32 v3, v2, v0
	v_sub_u32_e32 v1, v1, v3
	v_add_u32_e32 v5, 1, v2
	v_cmp_ge_u32_e32 vcc, v1, v0
	v_sub_u32_e32 v3, v1, v0
	s_nop 0
	v_cndmask_b32_e32 v2, v2, v5, vcc
	v_cndmask_b32_e32 v1, v1, v3, vcc
	v_add_u32_e32 v3, 1, v2
	v_cmp_ge_u32_e32 vcc, v1, v0
	s_nop 1
	v_cndmask_b32_e32 v2, v2, v3, vcc
	v_mul_lo_u32 v1, v0, v2
	v_add_u32_e32 v0, v1, v0
	v_cmp_ne_u32_e32 vcc, v4, v0
	v_mov_b64_e32 v[0:1], s[8:9]
	s_cbranch_vccnz .Lxg_3
	v_mov_b32_e32 v5, 1
	v_mov_b32_e32 v3, 0x82400
	global_atomic_add v3, v5, s[68:69]
	v_add_u32_e32 v3, 0x100, v3
	global_atomic_add v3, v5, s[68:69]
	v_add_u32_e32 v3, 0x100, v3
	global_atomic_add v3, v5, s[68:69]
	v_add_u32_e32 v3, 0x100, v3
	global_atomic_add v3, v5, s[68:69]
	v_add_u32_e32 v3, 0x100, v3
	global_atomic_add v3, v5, s[68:69]
	v_add_u32_e32 v3, 0x100, v3
	global_atomic_add v3, v5, s[68:69]
	v_add_u32_e32 v3, 0x100, v3
	global_atomic_add v3, v5, s[68:69]
	v_add_u32_e32 v3, 0x100, v3
	global_atomic_add v3, v5, s[68:69]
	v_add_u32_e32 v3, 0x100, v3
	global_atomic_add v3, v5, s[68:69]
	v_add_u32_e32 v3, 0x100, v3
	global_atomic_add v3, v5, s[68:69]
	v_add_u32_e32 v3, 0x100, v3
	global_atomic_add v3, v5, s[68:69]
	v_add_u32_e32 v3, 0x100, v3
	global_atomic_add v3, v5, s[68:69]
	v_add_u32_e32 v3, 0x100, v3
	global_atomic_add v3, v5, s[68:69]
	v_add_u32_e32 v3, 0x100, v3
	global_atomic_add v3, v5, s[68:69]
	v_add_u32_e32 v3, 0x100, v3
	global_atomic_add v3, v5, s[68:69]
	v_add_u32_e32 v3, 0x100, v3
	global_atomic_add v3, v5, s[68:69]
.Lxg_3:
	s_and_saveexec_b64 s[6:7], vcc
	s_cbranch_execz .LBB0_665
	v_mov_b32_e32 v0, 0
	global_load_dword v1, v0, s[8:9] sc1
	s_mov_b64 s[14:15], 0
	s_waitcnt vmcnt(0)
	v_cmp_eq_u32_e32 vcc, v1, v2
	s_and_saveexec_b64 s[12:13], vcc
	s_cbranch_execz .LBB0_664
	s_add_u32 s10, s68, 0x80200
	s_addc_u32 s11, s69, 0
	s_mov_b32 s3, 1
	s_branch .LBB0_657

; __device__ __forceinline__ unsigned xb_ld(unsigned* p)              { return __hip_atomic_load(p, __ATOMIC_RELAXED, __HIP_MEMORY_SCOPE_AGENT); }
; __device__ __forceinline__ unsigned xb_add(unsigned* p, unsigned v) { return __hip_atomic_fetch_add(p, v, __ATOMIC_RELAXED, __HIP_MEMORY_SCOPE_AGENT); }
; #define XB_SPIN(cond, bar) do { unsigned _sp = 0; while (cond) { __builtin_amdgcn_s_sleep(1); \
;     if ((++_sp & 255u) == 0u) { if (xb_ld(&(bar)[XB_TMO])) break; if (_sp > XB_SPIN_CAP) { atomicAdd(&(bar)[XB_TMO], 1u); break; } } } } while (0)
; __device__ __forceinline__ void xcd_barrier(const XcdBarrier& b) {
;     ...
;         const unsigned old = xb_add(&bar[XB_XSUB(b.x)], 1u);
;         const unsigned gen = old / nloc;
;         if (old + 1u == (gen + 1u) * nloc) {
;             __builtin_amdgcn_fence(__ATOMIC_RELEASE, "agent");
;             asm volatile("s_waitcnt vmcnt(0)" ::: "memory");
;             const unsigned og = xb_add(&bar[XB_TOP], 1u);
;             const unsigned tg = og / nx;
;             if (og + 1u == (tg + 1u) * nx) xb_add(&bar[XB_TOPGEN], 1u);
;             else XB_SPIN(xb_ld(&bar[XB_TOPGEN]) == tg, bar);
;             __builtin_amdgcn_fence(__ATOMIC_ACQUIRE, "agent");
;             xb_add(&bar[XB_XGEN(b.x)], 1u);
;             asm volatile("s_waitcnt vmcnt(0)" ::: "memory");
.LBB0_951:
	s_or_b64 exec, exec, s[14:15]
	v_cvt_f32_u32_e32 v3, v0
	s_waitcnt vmcnt(0)
	v_readfirstlane_b32 s3, v2
	s_add_u32 s14, s68, 0x83500
	s_addc_u32 s15, s69, 0
	v_rcp_iflag_f32_e32 v3, v3
	v_add_u32_e32 v1, s3, v1
	v_add_u32_e32 v4, 1, v1
	s_mov_b64 s[16:17], -1
	v_mul_f32_e32 v2, 0x4f7ffffe, v3
	v_cvt_u32_f32_e32 v2, v2
	v_sub_u32_e32 v3, 0, v0
	v_mul_lo_u32 v3, v3, v2
	v_mul_hi_u32 v3, v2, v3
	v_add_u32_e32 v2, v2, v3
	v_mul_hi_u32 v2, v1, v2
	v_mul_lo_u32 v3, v2, v0
	v_sub_u32_e32 v1, v1, v3
	v_add_u32_e32 v5, 1, v2
	v_cmp_ge_u32_e32 vcc, v1, v0
	v_sub_u32_e32 v3, v1, v0
	s_nop 0
	v_cndmask_b32_e32 v2, v2, v5, vcc
	v_cndmask_b32_e32 v1, v1, v3, vcc
	v_add_u32_e32 v3, 1, v2
	v_cmp_ge_u32_e32 vcc, v1, v0
	s_nop 1
	v_cndmask_b32_e32 v2, v2, v3, vcc
	v_mul_lo_u32 v1, v0, v2
	v_add_u32_e32 v0, v1, v0
	v_cmp_ne_u32_e32 vcc, v4, v0
	v_mov_b64_e32 v[0:1], s[14:15]
	s_cbranch_vccnz .Lxg_6
	v_mov_b32_e32 v5, 1
	v_mov_b32_e32 v3, 0x82400
	global_atomic_add v3, v5, s[68:69]
	v_add_u32_e32 v3, 0x100, v3
	global_atomic_add v3, v5, s[68:69]
	v_add_u32_e32 v3, 0x100, v3
	global_atomic_add v3, v5, s[68:69]
	v_add_u32_e32 v3, 0x100, v3
	global_atomic_add v3, v5, s[68:69]
	v_add_u32_e32 v3, 0x100, v3
	global_atomic_add v3, v5, s[68:69]
	v_add_u32_e32 v3, 0x100, v3
	global_atomic_add v3, v5, s[68:69]
	v_add_u32_e32 v3, 0x100, v3
	global_atomic_add v3, v5, s[68:69]
	v_add_u32_e32 v3, 0x100, v3
	global_atomic_add v3, v5, s[68:69]
	v_add_u32_e32 v3, 0x100, v3
	global_atomic_add v3, v5, s[68:69]
	v_add_u32_e32 v3, 0x100, v3
	global_atomic_add v3, v5, s[68:69]
	v_add_u32_e32 v3, 0x100, v3
	global_atomic_add v3, v5, s[68:69]
	v_add_u32_e32 v3, 0x100, v3
	global_atomic_add v3, v5, s[68:69]
	v_add_u32_e32 v3, 0x100, v3
	global_atomic_add v3, v5, s[68:69]
	v_add_u32_e32 v3, 0x100, v3
	global_atomic_add v3, v5, s[68:69]
	v_add_u32_e32 v3, 0x100, v3
	global_atomic_add v3, v5, s[68:69]
	v_add_u32_e32 v3, 0x100, v3
	global_atomic_add v3, v5, s[68:69]
.Lxg_6:
	s_and_saveexec_b64 s[12:13], vcc
	s_cbranch_execz .LBB0_963
	v_mov_b32_e32 v0, 0
	global_load_dword v1, v0, s[14:15] sc1
	s_mov_b64 s[20:21], 0
	s_waitcnt vmcnt(0)
	v_cmp_eq_u32_e32 vcc, v1, v2
	s_and_saveexec_b64 s[18:19], vcc
	s_cbranch_execz .LBB0_962
	s_add_u32 s16, s68, 0x80200
	s_addc_u32 s17, s69, 0
	s_mov_b32 s3, 1
	s_branch .LBB0_955

; __device__ __forceinline__ unsigned xb_add(unsigned* p, unsigned v) { return __hip_atomic_fetch_add(p, v, __ATOMIC_RELAXED, __HIP_MEMORY_SCOPE_AGENT); }
; __device__ __forceinline__ void xcd_barrier(const XcdBarrier& b) {
;     ...
;             xb_add(&bar[XB_XGEN(b.x)], 1u);
;             asm volatile("s_waitcnt vmcnt(0)" ::: "memory");
.LBB0_965:
	s_or_b64 exec, exec, s[12:13]
	s_mov_b64 s[12:13], exec
	v_mbcnt_lo_u32_b32 v0, s12, 0
	v_mbcnt_hi_u32_b32 v0, s13, v0
	v_cmp_eq_u32_e32 vcc, 0, v0
	s_waitcnt vmcnt(0)
	s_and_saveexec_b64 s[14:15], vcc
	s_cbranch_execz .LBB0_967
	s_bcnt1_i32_b64 s3, s[12:13]
	v_mov_b32_e32 v0, 0x2000
	v_mov_b32_e32 v1, s3
	s_nop 0

; __device__ __forceinline__ unsigned xb_ld(unsigned* p)              { return __hip_atomic_load(p, __ATOMIC_RELAXED, __HIP_MEMORY_SCOPE_AGENT); }
; __device__ __forceinline__ unsigned xb_add(unsigned* p, unsigned v) { return __hip_atomic_fetch_add(p, v, __ATOMIC_RELAXED, __HIP_MEMORY_SCOPE_AGENT); }
; #define XB_SPIN(cond, bar) do { unsigned _sp = 0; while (cond) { __builtin_amdgcn_s_sleep(1); \
;     if ((++_sp & 255u) == 0u) { if (xb_ld(&(bar)[XB_TMO])) break; if (_sp > XB_SPIN_CAP) { atomicAdd(&(bar)[XB_TMO], 1u); break; } } } } while (0)
; __device__ __forceinline__ void xcd_barrier(const XcdBarrier& b) {
;     ...
;         const unsigned old = xb_add(&bar[XB_XSUB(b.x)], 1u);
;         const unsigned gen = old / nloc;
;         if (old + 1u == (gen + 1u) * nloc) {
;             __builtin_amdgcn_fence(__ATOMIC_RELEASE, "agent");
;             asm volatile("s_waitcnt vmcnt(0)" ::: "memory");
;             const unsigned og = xb_add(&bar[XB_TOP], 1u);
;             const unsigned tg = og / nx;
;             if (og + 1u == (tg + 1u) * nx) xb_add(&bar[XB_TOPGEN], 1u);
;             else XB_SPIN(xb_ld(&bar[XB_TOPGEN]) == tg, bar);
;             __builtin_amdgcn_fence(__ATOMIC_ACQUIRE, "agent");
;             xb_add(&bar[XB_XGEN(b.x)], 1u);
;             asm volatile("s_waitcnt vmcnt(0)" ::: "memory");
.LBB0_1137:
	s_or_b64 exec, exec, s[8:9]
	v_cvt_f32_u32_e32 v3, v0
	s_waitcnt vmcnt(0)
	v_readfirstlane_b32 s4, v2
	s_add_u32 s8, s68, 0x83500
	s_addc_u32 s9, s69, 0
	v_rcp_iflag_f32_e32 v3, v3
	v_add_u32_e32 v1, s4, v1
	v_add_u32_e32 v4, 1, v1
	s_mov_b64 s[10:11], -1
	v_mul_f32_e32 v2, 0x4f7ffffe, v3
	v_cvt_u32_f32_e32 v2, v2
	v_sub_u32_e32 v3, 0, v0
	v_mul_lo_u32 v3, v3, v2
	v_mul_hi_u32 v3, v2, v3
	v_add_u32_e32 v2, v2, v3
	v_mul_hi_u32 v2, v1, v2
	v_mul_lo_u32 v3, v2, v0
	v_sub_u32_e32 v1, v1, v3
	v_add_u32_e32 v5, 1, v2
	v_cmp_ge_u32_e32 vcc, v1, v0
	v_sub_u32_e32 v3, v1, v0
	s_nop 0
	v_cndmask_b32_e32 v2, v2, v5, vcc
	v_cndmask_b32_e32 v1, v1, v3, vcc
	v_add_u32_e32 v3, 1, v2
	v_cmp_ge_u32_e32 vcc, v1, v0
	s_nop 1
	v_cndmask_b32_e32 v2, v2, v3, vcc
	v_mul_lo_u32 v1, v0, v2
	v_add_u32_e32 v0, v1, v0
	v_cmp_ne_u32_e32 vcc, v4, v0
	v_mov_b64_e32 v[0:1], s[8:9]
	s_cbranch_vccnz .Lxg_8
	v_mov_b32_e32 v5, 1
	v_mov_b32_e32 v3, 0x82400
	global_atomic_add v3, v5, s[68:69]
	v_add_u32_e32 v3, 0x100, v3
	global_atomic_add v3, v5, s[68:69]
	v_add_u32_e32 v3, 0x100, v3
	global_atomic_add v3, v5, s[68:69]
	v_add_u32_e32 v3, 0x100, v3
	global_atomic_add v3, v5, s[68:69]
	v_add_u32_e32 v3, 0x100, v3
	global_atomic_add v3, v5, s[68:69]
	v_add_u32_e32 v3, 0x100, v3
	global_atomic_add v3, v5, s[68:69]
	v_add_u32_e32 v3, 0x100, v3
	global_atomic_add v3, v5, s[68:69]
	v_add_u32_e32 v3, 0x100, v3
	global_atomic_add v3, v5, s[68:69]
	v_add_u32_e32 v3, 0x100, v3
	global_atomic_add v3, v5, s[68:69]
	v_add_u32_e32 v3, 0x100, v3
	global_atomic_add v3, v5, s[68:69]
	v_add_u32_e32 v3, 0x100, v3
	global_atomic_add v3, v5, s[68:69]
	v_add_u32_e32 v3, 0x100, v3
	global_atomic_add v3, v5, s[68:69]
	v_add_u32_e32 v3, 0x100, v3
	global_atomic_add v3, v5, s[68:69]
	v_add_u32_e32 v3, 0x100, v3
	global_atomic_add v3, v5, s[68:69]
	v_add_u32_e32 v3, 0x100, v3
	global_atomic_add v3, v5, s[68:69]
	v_add_u32_e32 v3, 0x100, v3
	global_atomic_add v3, v5, s[68:69]
.Lxg_8:
	s_and_saveexec_b64 s[4:5], vcc
	s_cbranch_execz .LBB0_1149
	v_mov_b32_e32 v0, 0
	global_load_dword v1, v0, s[8:9] sc1
	s_mov_b64 s[14:15], 0
	s_waitcnt vmcnt(0)
	v_cmp_eq_u32_e32 vcc, v1, v2
	s_and_saveexec_b64 s[12:13], vcc
	s_cbranch_execz .LBB0_1148
	s_add_u32 s10, s68, 0x80200
	s_addc_u32 s11, s69, 0
	s_mov_b32 s24, 1
	s_branch .LBB0_1141

; __device__ __forceinline__ unsigned xb_add(unsigned* p, unsigned v) { return __hip_atomic_fetch_add(p, v, __ATOMIC_RELAXED, __HIP_MEMORY_SCOPE_AGENT); }
; __device__ __forceinline__ void xcd_barrier(const XcdBarrier& b) {
;     ...
;             xb_add(&bar[XB_XGEN(b.x)], 1u);
;             asm volatile("s_waitcnt vmcnt(0)" ::: "memory");
.LBB0_1151:
	s_or_b64 exec, exec, s[4:5]
	s_mov_b64 s[4:5], exec
	v_mbcnt_lo_u32_b32 v0, s4, 0
	v_mbcnt_hi_u32_b32 v0, s5, v0
	v_cmp_eq_u32_e32 vcc, 0, v0
	s_waitcnt vmcnt(0)
	s_and_saveexec_b64 s[8:9], vcc
	s_cbranch_execz .LBB0_1153
	s_bcnt1_i32_b64 s4, s[4:5]
	v_mov_b32_e32 v0, 0x2000
	v_mov_b32_e32 v1, s4
	s_nop 0
